# cache-policy A/B: P3 pool-unit gate loads (read once) with nt
# speedup vs baseline: 1.0083x; 1.0083x over previous
.LBB0_557:
	v_mov_b64_e32 v[34:35], s[28:29]
	v_lshl_or_b32 v104, s8, 8, v140
	v_mad_i64_i32 v[34:35], s[10:11], v32, s18, v[34:35]
	v_ashrrev_i32_e32 v105, 31, v104
	v_lshl_add_u64 v[106:107], v[34:35], 0, s[4:5]
	v_lshlrev_b64 v[34:35], 1, v[104:105]
	v_or_b32_e32 v108, 16, v104
	v_lshl_add_u64 v[36:37], v[106:107], 0, v[34:35]
	v_ashrrev_i32_e32 v109, 31, v108
	v_or_b32_e32 v110, 32, v104
	v_or_b32_e32 v112, 48, v104
	s_waitcnt lgkmcnt(0)
	s_barrier
	v_mov_b32_e32 v170, v36
	v_mov_b32_e32 v171, v37
	v_lshlrev_b64 v[132:133], 12, v[32:33]
	v_lshl_add_u64 v[130:131], v[104:105], 2, s[60:61]
	v_lshl_add_u64 v[132:133], s[30:31], 0, v[132:133]
	v_mov_b32_e32 v64, v143
	v_add_u32_e32 v103, 0x10800, v143
	v_lshl_add_u64 v[132:133], v[104:105], 1, v[132:133]
	ds_read_b128 v[174:177], v64
	ds_read_b128 v[178:181], v64 offset:64
	ds_read_b128 v[182:185], v64 offset:128
	ds_read_b128 v[186:189], v64 offset:192
	ds_read_b128 v[190:193], v64 offset:256
	ds_read_b128 v[194:197], v64 offset:320
	ds_read_b128 v[198:201], v64 offset:384
	ds_read_b128 v[202:205], v64 offset:448
	global_load_dwordx2 v[32:33], v[170:171], off nt
	global_load_dwordx2 v[34:35], v[170:171], off offset:32 nt
	global_load_dwordx2 v[36:37], v[170:171], off offset:64 nt
	global_load_dwordx2 v[38:39], v[170:171], off offset:96 nt
	global_load_dwordx2 v[40:41], v[170:171], off offset:128 nt
	global_load_dwordx2 v[42:43], v[170:171], off offset:160 nt
	global_load_dwordx2 v[44:45], v[170:171], off offset:192 nt
	global_load_dwordx2 v[46:47], v[170:171], off offset:224 nt
	global_load_dwordx2 v[48:49], v[170:171], off offset:256 nt
	global_load_dwordx2 v[50:51], v[170:171], off offset:288 nt
	global_load_dwordx2 v[52:53], v[170:171], off offset:320 nt
	global_load_dwordx2 v[54:55], v[170:171], off offset:352 nt
	global_load_dwordx2 v[56:57], v[170:171], off offset:384 nt
	global_load_dwordx2 v[58:59], v[170:171], off offset:416 nt
	global_load_dwordx2 v[60:61], v[170:171], off offset:448 nt
	global_load_dwordx2 v[62:63], v[170:171], off offset:480 nt
	global_load_dwordx4 v[118:121], v[130:131], off
	global_load_dwordx4 v[122:125], v[130:131], off offset:64
	global_load_dwordx4 v[126:129], v[130:131], off offset:128
	s_waitcnt lgkmcnt(0)
	ds_read_b128 v[206:209], v64 offset:8448
	ds_read_b128 v[210:213], v64 offset:8512
	ds_read_b128 v[214:217], v64 offset:8576
	ds_read_b128 v[218:221], v64 offset:8640
	ds_read_b128 v[222:225], v64 offset:8704
	ds_read_b128 v[226:229], v64 offset:8768
	ds_read_b128 v[230:233], v64 offset:8832
	ds_read_b128 v[234:237], v64 offset:8896
	s_waitcnt vmcnt(26)
	v_mfma_f32_16x16x32_bf16 v[162:165], v[174:177], v[0:3], 0
	s_waitcnt vmcnt(25)
	v_mfma_f32_16x16x32_bf16 v[162:165], v[178:181], v[4:7], v[162:165]
	s_waitcnt vmcnt(24)
	v_mfma_f32_16x16x32_bf16 v[162:165], v[182:185], v[8:11], v[162:165]
	s_waitcnt vmcnt(23)
	v_mfma_f32_16x16x32_bf16 v[162:165], v[186:189], v[12:15], v[162:165]
	s_waitcnt vmcnt(22)
	v_mfma_f32_16x16x32_bf16 v[162:165], v[190:193], v[16:19], v[162:165]
	s_waitcnt vmcnt(21)
	v_mfma_f32_16x16x32_bf16 v[162:165], v[194:197], v[20:23], v[162:165]
	s_waitcnt vmcnt(20)
	v_mfma_f32_16x16x32_bf16 v[162:165], v[198:201], v[24:27], v[162:165]
	s_waitcnt vmcnt(19)
	v_mfma_f32_16x16x32_bf16 v[162:165], v[202:205], v[28:31], v[162:165]
	s_waitcnt vmcnt(18)
	v_lshlrev_b32_e32 v170, 16, v32
	v_and_b32_e32 v171, 0xffff0000, v32
	v_mul_f32_e32 v166, 0xbfb8aa3b, v170
	v_exp_f32_e32 v166, v166
	s_nop 0
	v_add_f32_e32 v166, 1.0, v166
	v_rcp_f32_e32 v172, v166
	v_mul_f32_e32 v166, 0xbfb8aa3b, v171
	v_exp_f32_e32 v166, v166
	s_nop 0
	v_add_f32_e32 v166, 1.0, v166
	v_rcp_f32_e32 v173, v166
	s_waitcnt vmcnt(2)
	v_pk_mul_f32 v[118:119], v[118:119], v[162:163]
	v_pk_mul_f32 v[120:121], v[120:121], v[164:165]
	v_pk_mul_f32 v[172:173], v[172:173], v[170:171]
	s_nop 0
	v_pk_mul_f32 v[118:119], v[172:173], v[118:119]
	s_nop 0
	v_cvt_pk_bf16_f32 v166, v118, v119
	v_lshlrev_b32_e32 v170, 16, v33
	v_and_b32_e32 v171, 0xffff0000, v33
	v_mul_f32_e32 v167, 0xbfb8aa3b, v170
	v_exp_f32_e32 v167, v167
	s_nop 0
	v_add_f32_e32 v167, 1.0, v167
	v_rcp_f32_e32 v172, v167
	v_mul_f32_e32 v167, 0xbfb8aa3b, v171
	v_exp_f32_e32 v167, v167
	s_nop 0
	v_add_f32_e32 v167, 1.0, v167
	v_rcp_f32_e32 v173, v167
	s_nop 1
	v_pk_mul_f32 v[172:173], v[172:173], v[170:171]
	s_nop 0
	v_pk_mul_f32 v[120:121], v[172:173], v[120:121]
	s_nop 0
	v_cvt_pk_bf16_f32 v167, v120, v121
	s_nop 0
	global_store_dwordx2 v[132:133], v[166:167], off offset:2048
	global_load_dwordx4 v[118:121], v[130:131], off offset:192
	s_waitcnt lgkmcnt(0)
	ds_read_b128 v[174:177], v64 offset:16896
	ds_read_b128 v[178:181], v64 offset:16960
	ds_read_b128 v[182:185], v64 offset:17024
	ds_read_b128 v[186:189], v64 offset:17088
	ds_read_b128 v[190:193], v64 offset:17152
	ds_read_b128 v[194:197], v64 offset:17216
	ds_read_b128 v[198:201], v64 offset:17280
	ds_read_b128 v[202:205], v64 offset:17344
	v_mfma_f32_16x16x32_bf16 v[162:165], v[206:209], v[0:3], 0
	v_mfma_f32_16x16x32_bf16 v[162:165], v[210:213], v[4:7], v[162:165]
	v_mfma_f32_16x16x32_bf16 v[162:165], v[214:217], v[8:11], v[162:165]
	v_mfma_f32_16x16x32_bf16 v[162:165], v[218:221], v[12:15], v[162:165]
	v_mfma_f32_16x16x32_bf16 v[162:165], v[222:225], v[16:19], v[162:165]
	v_mfma_f32_16x16x32_bf16 v[162:165], v[226:229], v[20:23], v[162:165]
	v_mfma_f32_16x16x32_bf16 v[162:165], v[230:233], v[24:27], v[162:165]
	v_mfma_f32_16x16x32_bf16 v[162:165], v[234:237], v[28:31], v[162:165]
	s_waitcnt vmcnt(19)
	v_lshlrev_b32_e32 v170, 16, v34
	v_and_b32_e32 v171, 0xffff0000, v34
	v_mul_f32_e32 v166, 0xbfb8aa3b, v170
	v_exp_f32_e32 v166, v166
	s_nop 0
	v_add_f32_e32 v166, 1.0, v166
	v_rcp_f32_e32 v172, v166
	v_mul_f32_e32 v166, 0xbfb8aa3b, v171
	v_exp_f32_e32 v166, v166
	s_nop 0
	v_add_f32_e32 v166, 1.0, v166
	v_rcp_f32_e32 v173, v166
	s_waitcnt vmcnt(3)
	v_pk_mul_f32 v[122:123], v[122:123], v[162:163]
	v_pk_mul_f32 v[124:125], v[124:125], v[164:165]
	v_pk_mul_f32 v[172:173], v[172:173], v[170:171]
	s_nop 0
	v_pk_mul_f32 v[122:123], v[172:173], v[122:123]
	s_nop 0
	v_cvt_pk_bf16_f32 v166, v122, v123
	v_lshlrev_b32_e32 v170, 16, v35
	v_and_b32_e32 v171, 0xffff0000, v35
	v_mul_f32_e32 v167, 0xbfb8aa3b, v170
	v_exp_f32_e32 v167, v167
	s_nop 0
	v_add_f32_e32 v167, 1.0, v167
	v_rcp_f32_e32 v172, v167
	v_mul_f32_e32 v167, 0xbfb8aa3b, v171
	v_exp_f32_e32 v167, v167
	s_nop 0
	v_add_f32_e32 v167, 1.0, v167
	v_rcp_f32_e32 v173, v167
	s_nop 1
	v_pk_mul_f32 v[172:173], v[172:173], v[170:171]
	s_nop 0
	v_pk_mul_f32 v[124:125], v[172:173], v[124:125]
	s_nop 0
	v_cvt_pk_bf16_f32 v167, v124, v125
	s_nop 0
	global_store_dwordx2 v[132:133], v[166:167], off offset:2080
	global_load_dwordx4 v[122:125], v[130:131], off offset:256
	s_waitcnt lgkmcnt(0)
	ds_read_b128 v[206:209], v64 offset:25344
	ds_read_b128 v[210:213], v64 offset:25408
	ds_read_b128 v[214:217], v64 offset:25472
	ds_read_b128 v[218:221], v64 offset:25536
	ds_read_b128 v[222:225], v64 offset:25600
	ds_read_b128 v[226:229], v64 offset:25664
	ds_read_b128 v[230:233], v64 offset:25728
	ds_read_b128 v[234:237], v64 offset:25792
	v_mfma_f32_16x16x32_bf16 v[162:165], v[174:177], v[0:3], 0
	v_mfma_f32_16x16x32_bf16 v[162:165], v[178:181], v[4:7], v[162:165]
	v_mfma_f32_16x16x32_bf16 v[162:165], v[182:185], v[8:11], v[162:165]
	v_mfma_f32_16x16x32_bf16 v[162:165], v[186:189], v[12:15], v[162:165]
	v_mfma_f32_16x16x32_bf16 v[162:165], v[190:193], v[16:19], v[162:165]
	v_mfma_f32_16x16x32_bf16 v[162:165], v[194:197], v[20:23], v[162:165]
	v_mfma_f32_16x16x32_bf16 v[162:165], v[198:201], v[24:27], v[162:165]
	v_mfma_f32_16x16x32_bf16 v[162:165], v[202:205], v[28:31], v[162:165]
	s_waitcnt vmcnt(20)
	v_lshlrev_b32_e32 v170, 16, v36
	v_and_b32_e32 v171, 0xffff0000, v36
	v_mul_f32_e32 v166, 0xbfb8aa3b, v170
	v_exp_f32_e32 v166, v166
	s_nop 0
	v_add_f32_e32 v166, 1.0, v166
	v_rcp_f32_e32 v172, v166
	v_mul_f32_e32 v166, 0xbfb8aa3b, v171
	v_exp_f32_e32 v166, v166
	s_nop 0
	v_add_f32_e32 v166, 1.0, v166
	v_rcp_f32_e32 v173, v166
	s_waitcnt vmcnt(4)
	v_pk_mul_f32 v[126:127], v[126:127], v[162:163]
	v_pk_mul_f32 v[128:129], v[128:129], v[164:165]
	v_pk_mul_f32 v[172:173], v[172:173], v[170:171]
	s_nop 0
	v_pk_mul_f32 v[126:127], v[172:173], v[126:127]
	s_nop 0
	v_cvt_pk_bf16_f32 v166, v126, v127
	v_lshlrev_b32_e32 v170, 16, v37
	v_and_b32_e32 v171, 0xffff0000, v37
	v_mul_f32_e32 v167, 0xbfb8aa3b, v170
	v_exp_f32_e32 v167, v167
	s_nop 0
	v_add_f32_e32 v167, 1.0, v167
	v_rcp_f32_e32 v172, v167
	v_mul_f32_e32 v167, 0xbfb8aa3b, v171
	v_exp_f32_e32 v167, v167
	s_nop 0
	v_add_f32_e32 v167, 1.0, v167
	v_rcp_f32_e32 v173, v167
	s_nop 1
	v_pk_mul_f32 v[172:173], v[172:173], v[170:171]
	s_nop 0
	v_pk_mul_f32 v[128:129], v[172:173], v[128:129]
	s_nop 0
	v_cvt_pk_bf16_f32 v167, v128, v129
	s_nop 0
	global_store_dwordx2 v[132:133], v[166:167], off offset:2112
	global_load_dwordx4 v[126:129], v[130:131], off offset:320
	s_waitcnt lgkmcnt(0)
	ds_read_b128 v[174:177], v64 offset:33792
	ds_read_b128 v[178:181], v64 offset:33856
	ds_read_b128 v[182:185], v64 offset:33920
	ds_read_b128 v[186:189], v64 offset:33984
	ds_read_b128 v[190:193], v64 offset:34048
	ds_read_b128 v[194:197], v64 offset:34112
	ds_read_b128 v[198:201], v64 offset:34176
	ds_read_b128 v[202:205], v64 offset:34240
	v_mfma_f32_16x16x32_bf16 v[162:165], v[206:209], v[0:3], 0
	v_mfma_f32_16x16x32_bf16 v[162:165], v[210:213], v[4:7], v[162:165]
	v_mfma_f32_16x16x32_bf16 v[162:165], v[214:217], v[8:11], v[162:165]
	v_mfma_f32_16x16x32_bf16 v[162:165], v[218:221], v[12:15], v[162:165]
	v_mfma_f32_16x16x32_bf16 v[162:165], v[222:225], v[16:19], v[162:165]
	v_mfma_f32_16x16x32_bf16 v[162:165], v[226:229], v[20:23], v[162:165]
	v_mfma_f32_16x16x32_bf16 v[162:165], v[230:233], v[24:27], v[162:165]
	v_mfma_f32_16x16x32_bf16 v[162:165], v[234:237], v[28:31], v[162:165]
	s_waitcnt vmcnt(21)
	v_lshlrev_b32_e32 v170, 16, v38
	v_and_b32_e32 v171, 0xffff0000, v38
	v_mul_f32_e32 v166, 0xbfb8aa3b, v170
	v_exp_f32_e32 v166, v166
	s_nop 0
	v_add_f32_e32 v166, 1.0, v166
	v_rcp_f32_e32 v172, v166
	v_mul_f32_e32 v166, 0xbfb8aa3b, v171
	v_exp_f32_e32 v166, v166
	s_nop 0
	v_add_f32_e32 v166, 1.0, v166
	v_rcp_f32_e32 v173, v166
	s_waitcnt vmcnt(4)
	v_pk_mul_f32 v[118:119], v[118:119], v[162:163]
	v_pk_mul_f32 v[120:121], v[120:121], v[164:165]
	v_pk_mul_f32 v[172:173], v[172:173], v[170:171]
	s_nop 0
	v_pk_mul_f32 v[118:119], v[172:173], v[118:119]
	s_nop 0
	v_cvt_pk_bf16_f32 v166, v118, v119
	v_lshlrev_b32_e32 v170, 16, v39
	v_and_b32_e32 v171, 0xffff0000, v39
	v_mul_f32_e32 v167, 0xbfb8aa3b, v170
	v_exp_f32_e32 v167, v167
	s_nop 0
	v_add_f32_e32 v167, 1.0, v167
	v_rcp_f32_e32 v172, v167
	v_mul_f32_e32 v167, 0xbfb8aa3b, v171
	v_exp_f32_e32 v167, v167
	s_nop 0
	v_add_f32_e32 v167, 1.0, v167
	v_rcp_f32_e32 v173, v167
	s_nop 1
	v_pk_mul_f32 v[172:173], v[172:173], v[170:171]
	s_nop 0
	v_pk_mul_f32 v[120:121], v[172:173], v[120:121]
	s_nop 0
	v_cvt_pk_bf16_f32 v167, v120, v121
	s_nop 0
	global_store_dwordx2 v[132:133], v[166:167], off offset:2144
	global_load_dwordx4 v[118:121], v[130:131], off offset:384
	s_waitcnt lgkmcnt(0)
	ds_read_b128 v[206:209], v64 offset:42240
	ds_read_b128 v[210:213], v64 offset:42304
	ds_read_b128 v[214:217], v64 offset:42368
	ds_read_b128 v[218:221], v64 offset:42432
	ds_read_b128 v[222:225], v64 offset:42496
	ds_read_b128 v[226:229], v64 offset:42560
	ds_read_b128 v[230:233], v64 offset:42624
	ds_read_b128 v[234:237], v64 offset:42688
	v_mfma_f32_16x16x32_bf16 v[162:165], v[174:177], v[0:3], 0
	v_mfma_f32_16x16x32_bf16 v[162:165], v[178:181], v[4:7], v[162:165]
	v_mfma_f32_16x16x32_bf16 v[162:165], v[182:185], v[8:11], v[162:165]
	v_mfma_f32_16x16x32_bf16 v[162:165], v[186:189], v[12:15], v[162:165]
	v_mfma_f32_16x16x32_bf16 v[162:165], v[190:193], v[16:19], v[162:165]
	v_mfma_f32_16x16x32_bf16 v[162:165], v[194:197], v[20:23], v[162:165]
	v_mfma_f32_16x16x32_bf16 v[162:165], v[198:201], v[24:27], v[162:165]
	v_mfma_f32_16x16x32_bf16 v[162:165], v[202:205], v[28:31], v[162:165]
	s_waitcnt vmcnt(22)
	v_lshlrev_b32_e32 v170, 16, v40
	v_and_b32_e32 v171, 0xffff0000, v40
	v_mul_f32_e32 v166, 0xbfb8aa3b, v170
	v_exp_f32_e32 v166, v166
	s_nop 0
	v_add_f32_e32 v166, 1.0, v166
	v_rcp_f32_e32 v172, v166
	v_mul_f32_e32 v166, 0xbfb8aa3b, v171
	v_exp_f32_e32 v166, v166
	s_nop 0
	v_add_f32_e32 v166, 1.0, v166
	v_rcp_f32_e32 v173, v166
	s_waitcnt vmcnt(4)
	v_pk_mul_f32 v[122:123], v[122:123], v[162:163]
	v_pk_mul_f32 v[124:125], v[124:125], v[164:165]
	v_pk_mul_f32 v[172:173], v[172:173], v[170:171]
	s_nop 0
	v_pk_mul_f32 v[122:123], v[172:173], v[122:123]
	s_nop 0
	v_cvt_pk_bf16_f32 v166, v122, v123
	v_lshlrev_b32_e32 v170, 16, v41
	v_and_b32_e32 v171, 0xffff0000, v41
	v_mul_f32_e32 v167, 0xbfb8aa3b, v170
	v_exp_f32_e32 v167, v167
	s_nop 0
	v_add_f32_e32 v167, 1.0, v167
	v_rcp_f32_e32 v172, v167
	v_mul_f32_e32 v167, 0xbfb8aa3b, v171
	v_exp_f32_e32 v167, v167
	s_nop 0
	v_add_f32_e32 v167, 1.0, v167
	v_rcp_f32_e32 v173, v167
	s_nop 1
	v_pk_mul_f32 v[172:173], v[172:173], v[170:171]
	s_nop 0
	v_pk_mul_f32 v[124:125], v[172:173], v[124:125]
	s_nop 0
	v_cvt_pk_bf16_f32 v167, v124, v125
	s_nop 0
	global_store_dwordx2 v[132:133], v[166:167], off offset:2176
	global_load_dwordx4 v[122:125], v[130:131], off offset:448
	s_waitcnt lgkmcnt(0)
	ds_read_b128 v[174:177], v64 offset:50688
	ds_read_b128 v[178:181], v64 offset:50752
	ds_read_b128 v[182:185], v64 offset:50816
	ds_read_b128 v[186:189], v64 offset:50880
	ds_read_b128 v[190:193], v64 offset:50944
	ds_read_b128 v[194:197], v64 offset:51008
	ds_read_b128 v[198:201], v64 offset:51072
	ds_read_b128 v[202:205], v64 offset:51136
	v_mfma_f32_16x16x32_bf16 v[162:165], v[206:209], v[0:3], 0
	v_mfma_f32_16x16x32_bf16 v[162:165], v[210:213], v[4:7], v[162:165]
	v_mfma_f32_16x16x32_bf16 v[162:165], v[214:217], v[8:11], v[162:165]
	v_mfma_f32_16x16x32_bf16 v[162:165], v[218:221], v[12:15], v[162:165]
	v_mfma_f32_16x16x32_bf16 v[162:165], v[222:225], v[16:19], v[162:165]
	v_mfma_f32_16x16x32_bf16 v[162:165], v[226:229], v[20:23], v[162:165]
	v_mfma_f32_16x16x32_bf16 v[162:165], v[230:233], v[24:27], v[162:165]
	v_mfma_f32_16x16x32_bf16 v[162:165], v[234:237], v[28:31], v[162:165]
	s_waitcnt vmcnt(23)
	v_lshlrev_b32_e32 v170, 16, v42
	v_and_b32_e32 v171, 0xffff0000, v42
	v_mul_f32_e32 v166, 0xbfb8aa3b, v170
	v_exp_f32_e32 v166, v166
	s_nop 0
	v_add_f32_e32 v166, 1.0, v166
	v_rcp_f32_e32 v172, v166
	v_mul_f32_e32 v166, 0xbfb8aa3b, v171
	v_exp_f32_e32 v166, v166
	s_nop 0
	v_add_f32_e32 v166, 1.0, v166
	v_rcp_f32_e32 v173, v166
	s_waitcnt vmcnt(4)
	v_pk_mul_f32 v[126:127], v[126:127], v[162:163]
	v_pk_mul_f32 v[128:129], v[128:129], v[164:165]
	v_pk_mul_f32 v[172:173], v[172:173], v[170:171]
	s_nop 0
	v_pk_mul_f32 v[126:127], v[172:173], v[126:127]
	s_nop 0
	v_cvt_pk_bf16_f32 v166, v126, v127
	v_lshlrev_b32_e32 v170, 16, v43
	v_and_b32_e32 v171, 0xffff0000, v43
	v_mul_f32_e32 v167, 0xbfb8aa3b, v170
	v_exp_f32_e32 v167, v167
	s_nop 0
	v_add_f32_e32 v167, 1.0, v167
	v_rcp_f32_e32 v172, v167
	v_mul_f32_e32 v167, 0xbfb8aa3b, v171
	v_exp_f32_e32 v167, v167
	s_nop 0
	v_add_f32_e32 v167, 1.0, v167
	v_rcp_f32_e32 v173, v167
	s_nop 1
	v_pk_mul_f32 v[172:173], v[172:173], v[170:171]
	s_nop 0
	v_pk_mul_f32 v[128:129], v[172:173], v[128:129]
	s_nop 0
	v_cvt_pk_bf16_f32 v167, v128, v129
	s_nop 0
	global_store_dwordx2 v[132:133], v[166:167], off offset:2208
	global_load_dwordx4 v[126:129], v[130:131], off offset:512
	s_waitcnt lgkmcnt(0)
	ds_read_b128 v[206:209], v64 offset:59136
	ds_read_b128 v[210:213], v64 offset:59200
	ds_read_b128 v[214:217], v64 offset:59264
	ds_read_b128 v[218:221], v64 offset:59328
	ds_read_b128 v[222:225], v64 offset:59392
	ds_read_b128 v[226:229], v64 offset:59456
	ds_read_b128 v[230:233], v64 offset:59520
	ds_read_b128 v[234:237], v64 offset:59584
	v_mfma_f32_16x16x32_bf16 v[162:165], v[174:177], v[0:3], 0
	v_mfma_f32_16x16x32_bf16 v[162:165], v[178:181], v[4:7], v[162:165]
	v_mfma_f32_16x16x32_bf16 v[162:165], v[182:185], v[8:11], v[162:165]
	v_mfma_f32_16x16x32_bf16 v[162:165], v[186:189], v[12:15], v[162:165]
	v_mfma_f32_16x16x32_bf16 v[162:165], v[190:193], v[16:19], v[162:165]
	v_mfma_f32_16x16x32_bf16 v[162:165], v[194:197], v[20:23], v[162:165]
	v_mfma_f32_16x16x32_bf16 v[162:165], v[198:201], v[24:27], v[162:165]
	v_mfma_f32_16x16x32_bf16 v[162:165], v[202:205], v[28:31], v[162:165]
	s_waitcnt vmcnt(24)
	v_lshlrev_b32_e32 v170, 16, v44
	v_and_b32_e32 v171, 0xffff0000, v44
	v_mul_f32_e32 v166, 0xbfb8aa3b, v170
	v_exp_f32_e32 v166, v166
	s_nop 0
	v_add_f32_e32 v166, 1.0, v166
	v_rcp_f32_e32 v172, v166
	v_mul_f32_e32 v166, 0xbfb8aa3b, v171
	v_exp_f32_e32 v166, v166
	s_nop 0
	v_add_f32_e32 v166, 1.0, v166
	v_rcp_f32_e32 v173, v166
	s_waitcnt vmcnt(4)
	v_pk_mul_f32 v[118:119], v[118:119], v[162:163]
	v_pk_mul_f32 v[120:121], v[120:121], v[164:165]
	v_pk_mul_f32 v[172:173], v[172:173], v[170:171]
	s_nop 0
	v_pk_mul_f32 v[118:119], v[172:173], v[118:119]
	s_nop 0
	v_cvt_pk_bf16_f32 v166, v118, v119
	v_lshlrev_b32_e32 v170, 16, v45
	v_and_b32_e32 v171, 0xffff0000, v45
	v_mul_f32_e32 v167, 0xbfb8aa3b, v170
	v_exp_f32_e32 v167, v167
	s_nop 0
	v_add_f32_e32 v167, 1.0, v167
	v_rcp_f32_e32 v172, v167
	v_mul_f32_e32 v167, 0xbfb8aa3b, v171
	v_exp_f32_e32 v167, v167
	s_nop 0
	v_add_f32_e32 v167, 1.0, v167
	v_rcp_f32_e32 v173, v167
	s_nop 1
	v_pk_mul_f32 v[172:173], v[172:173], v[170:171]
	s_nop 0
	v_pk_mul_f32 v[120:121], v[172:173], v[120:121]
	s_nop 0
	v_cvt_pk_bf16_f32 v167, v120, v121
	s_nop 0
	global_store_dwordx2 v[132:133], v[166:167], off offset:2240
	global_load_dwordx4 v[118:121], v[130:131], off offset:576
	s_waitcnt lgkmcnt(0)
	ds_read_b128 v[174:177], v103
	ds_read_b128 v[178:181], v103 offset:64
	ds_read_b128 v[182:185], v103 offset:128
	ds_read_b128 v[186:189], v103 offset:192
	ds_read_b128 v[190:193], v103 offset:256
	ds_read_b128 v[194:197], v103 offset:320
	ds_read_b128 v[198:201], v103 offset:384
	ds_read_b128 v[202:205], v103 offset:448
	v_mfma_f32_16x16x32_bf16 v[162:165], v[206:209], v[0:3], 0
	v_mfma_f32_16x16x32_bf16 v[162:165], v[210:213], v[4:7], v[162:165]
	v_mfma_f32_16x16x32_bf16 v[162:165], v[214:217], v[8:11], v[162:165]
	v_mfma_f32_16x16x32_bf16 v[162:165], v[218:221], v[12:15], v[162:165]
	v_mfma_f32_16x16x32_bf16 v[162:165], v[222:225], v[16:19], v[162:165]
	v_mfma_f32_16x16x32_bf16 v[162:165], v[226:229], v[20:23], v[162:165]
	v_mfma_f32_16x16x32_bf16 v[162:165], v[230:233], v[24:27], v[162:165]
	v_mfma_f32_16x16x32_bf16 v[162:165], v[234:237], v[28:31], v[162:165]
	s_waitcnt vmcnt(25)
	v_lshlrev_b32_e32 v170, 16, v46
	v_and_b32_e32 v171, 0xffff0000, v46
	v_mul_f32_e32 v166, 0xbfb8aa3b, v170
	v_exp_f32_e32 v166, v166
	s_nop 0
	v_add_f32_e32 v166, 1.0, v166
	v_rcp_f32_e32 v172, v166
	v_mul_f32_e32 v166, 0xbfb8aa3b, v171
	v_exp_f32_e32 v166, v166
	s_nop 0
	v_add_f32_e32 v166, 1.0, v166
	v_rcp_f32_e32 v173, v166
	s_waitcnt vmcnt(4)
	v_pk_mul_f32 v[122:123], v[122:123], v[162:163]
	v_pk_mul_f32 v[124:125], v[124:125], v[164:165]
	v_pk_mul_f32 v[172:173], v[172:173], v[170:171]
	s_nop 0
	v_pk_mul_f32 v[122:123], v[172:173], v[122:123]
	s_nop 0
	v_cvt_pk_bf16_f32 v166, v122, v123
	v_lshlrev_b32_e32 v170, 16, v47
	v_and_b32_e32 v171, 0xffff0000, v47
	v_mul_f32_e32 v167, 0xbfb8aa3b, v170
	v_exp_f32_e32 v167, v167
	s_nop 0
	v_add_f32_e32 v167, 1.0, v167
	v_rcp_f32_e32 v172, v167
	v_mul_f32_e32 v167, 0xbfb8aa3b, v171
	v_exp_f32_e32 v167, v167
	s_nop 0
	v_add_f32_e32 v167, 1.0, v167
	v_rcp_f32_e32 v173, v167
	s_nop 1
	v_pk_mul_f32 v[172:173], v[172:173], v[170:171]
	s_nop 0
	v_pk_mul_f32 v[124:125], v[172:173], v[124:125]
	s_nop 0
	v_cvt_pk_bf16_f32 v167, v124, v125
	s_nop 0
	global_store_dwordx2 v[132:133], v[166:167], off offset:2272
	global_load_dwordx4 v[122:125], v[130:131], off offset:640
	s_waitcnt lgkmcnt(0)
	ds_read_b128 v[206:209], v103 offset:8448
	ds_read_b128 v[210:213], v103 offset:8512
	ds_read_b128 v[214:217], v103 offset:8576
	ds_read_b128 v[218:221], v103 offset:8640
	ds_read_b128 v[222:225], v103 offset:8704
	ds_read_b128 v[226:229], v103 offset:8768
	ds_read_b128 v[230:233], v103 offset:8832
	ds_read_b128 v[234:237], v103 offset:8896
	v_mfma_f32_16x16x32_bf16 v[162:165], v[174:177], v[0:3], 0
	v_mfma_f32_16x16x32_bf16 v[162:165], v[178:181], v[4:7], v[162:165]
	v_mfma_f32_16x16x32_bf16 v[162:165], v[182:185], v[8:11], v[162:165]
	v_mfma_f32_16x16x32_bf16 v[162:165], v[186:189], v[12:15], v[162:165]
	v_mfma_f32_16x16x32_bf16 v[162:165], v[190:193], v[16:19], v[162:165]
	v_mfma_f32_16x16x32_bf16 v[162:165], v[194:197], v[20:23], v[162:165]
	v_mfma_f32_16x16x32_bf16 v[162:165], v[198:201], v[24:27], v[162:165]
	v_mfma_f32_16x16x32_bf16 v[162:165], v[202:205], v[28:31], v[162:165]
	s_waitcnt vmcnt(26)
	v_lshlrev_b32_e32 v170, 16, v48
	v_and_b32_e32 v171, 0xffff0000, v48
	v_mul_f32_e32 v166, 0xbfb8aa3b, v170
	v_exp_f32_e32 v166, v166
	s_nop 0
	v_add_f32_e32 v166, 1.0, v166
	v_rcp_f32_e32 v172, v166
	v_mul_f32_e32 v166, 0xbfb8aa3b, v171
	v_exp_f32_e32 v166, v166
	s_nop 0
	v_add_f32_e32 v166, 1.0, v166
	v_rcp_f32_e32 v173, v166
	s_waitcnt vmcnt(4)
	v_pk_mul_f32 v[126:127], v[126:127], v[162:163]
	v_pk_mul_f32 v[128:129], v[128:129], v[164:165]
	v_pk_mul_f32 v[172:173], v[172:173], v[170:171]
	s_nop 0
	v_pk_mul_f32 v[126:127], v[172:173], v[126:127]
	s_nop 0
	v_cvt_pk_bf16_f32 v166, v126, v127
	v_lshlrev_b32_e32 v170, 16, v49
	v_and_b32_e32 v171, 0xffff0000, v49
	v_mul_f32_e32 v167, 0xbfb8aa3b, v170
	v_exp_f32_e32 v167, v167
	s_nop 0
	v_add_f32_e32 v167, 1.0, v167
	v_rcp_f32_e32 v172, v167
	v_mul_f32_e32 v167, 0xbfb8aa3b, v171
	v_exp_f32_e32 v167, v167
	s_nop 0
	v_add_f32_e32 v167, 1.0, v167
	v_rcp_f32_e32 v173, v167
	s_nop 1
	v_pk_mul_f32 v[172:173], v[172:173], v[170:171]
	s_nop 0
	v_pk_mul_f32 v[128:129], v[172:173], v[128:129]
	s_nop 0
	v_cvt_pk_bf16_f32 v167, v128, v129
	s_nop 0
	global_store_dwordx2 v[132:133], v[166:167], off offset:2304
	global_load_dwordx4 v[126:129], v[130:131], off offset:704
	s_waitcnt lgkmcnt(0)
	ds_read_b128 v[174:177], v103 offset:16896
	ds_read_b128 v[178:181], v103 offset:16960
	ds_read_b128 v[182:185], v103 offset:17024
	ds_read_b128 v[186:189], v103 offset:17088
	ds_read_b128 v[190:193], v103 offset:17152
	ds_read_b128 v[194:197], v103 offset:17216
	ds_read_b128 v[198:201], v103 offset:17280
	ds_read_b128 v[202:205], v103 offset:17344
	v_mfma_f32_16x16x32_bf16 v[162:165], v[206:209], v[0:3], 0
	v_mfma_f32_16x16x32_bf16 v[162:165], v[210:213], v[4:7], v[162:165]
	v_mfma_f32_16x16x32_bf16 v[162:165], v[214:217], v[8:11], v[162:165]
	v_mfma_f32_16x16x32_bf16 v[162:165], v[218:221], v[12:15], v[162:165]
	v_mfma_f32_16x16x32_bf16 v[162:165], v[222:225], v[16:19], v[162:165]
	v_mfma_f32_16x16x32_bf16 v[162:165], v[226:229], v[20:23], v[162:165]
	v_mfma_f32_16x16x32_bf16 v[162:165], v[230:233], v[24:27], v[162:165]
	v_mfma_f32_16x16x32_bf16 v[162:165], v[234:237], v[28:31], v[162:165]
	s_waitcnt vmcnt(27)
	v_lshlrev_b32_e32 v170, 16, v50
	v_and_b32_e32 v171, 0xffff0000, v50
	v_mul_f32_e32 v166, 0xbfb8aa3b, v170
	v_exp_f32_e32 v166, v166
	s_nop 0
	v_add_f32_e32 v166, 1.0, v166
	v_rcp_f32_e32 v172, v166
	v_mul_f32_e32 v166, 0xbfb8aa3b, v171
	v_exp_f32_e32 v166, v166
	s_nop 0
	v_add_f32_e32 v166, 1.0, v166
	v_rcp_f32_e32 v173, v166
	s_waitcnt vmcnt(4)
	v_pk_mul_f32 v[118:119], v[118:119], v[162:163]
	v_pk_mul_f32 v[120:121], v[120:121], v[164:165]
	v_pk_mul_f32 v[172:173], v[172:173], v[170:171]
	s_nop 0
	v_pk_mul_f32 v[118:119], v[172:173], v[118:119]
	s_nop 0
	v_cvt_pk_bf16_f32 v166, v118, v119
	v_lshlrev_b32_e32 v170, 16, v51
	v_and_b32_e32 v171, 0xffff0000, v51
	v_mul_f32_e32 v167, 0xbfb8aa3b, v170
	v_exp_f32_e32 v167, v167
	s_nop 0
	v_add_f32_e32 v167, 1.0, v167
	v_rcp_f32_e32 v172, v167
	v_mul_f32_e32 v167, 0xbfb8aa3b, v171
	v_exp_f32_e32 v167, v167
	s_nop 0
	v_add_f32_e32 v167, 1.0, v167
	v_rcp_f32_e32 v173, v167
	s_nop 1
	v_pk_mul_f32 v[172:173], v[172:173], v[170:171]
	s_nop 0
	v_pk_mul_f32 v[120:121], v[172:173], v[120:121]
	s_nop 0
	v_cvt_pk_bf16_f32 v167, v120, v121
	s_nop 0
	global_store_dwordx2 v[132:133], v[166:167], off offset:2336
	global_load_dwordx4 v[118:121], v[130:131], off offset:768
	s_waitcnt lgkmcnt(0)
	ds_read_b128 v[206:209], v103 offset:25344
	ds_read_b128 v[210:213], v103 offset:25408
	ds_read_b128 v[214:217], v103 offset:25472
	ds_read_b128 v[218:221], v103 offset:25536
	ds_read_b128 v[222:225], v103 offset:25600
	ds_read_b128 v[226:229], v103 offset:25664
	ds_read_b128 v[230:233], v103 offset:25728
	ds_read_b128 v[234:237], v103 offset:25792
	v_mfma_f32_16x16x32_bf16 v[162:165], v[174:177], v[0:3], 0
	v_mfma_f32_16x16x32_bf16 v[162:165], v[178:181], v[4:7], v[162:165]
	v_mfma_f32_16x16x32_bf16 v[162:165], v[182:185], v[8:11], v[162:165]
	v_mfma_f32_16x16x32_bf16 v[162:165], v[186:189], v[12:15], v[162:165]
	v_mfma_f32_16x16x32_bf16 v[162:165], v[190:193], v[16:19], v[162:165]
	v_mfma_f32_16x16x32_bf16 v[162:165], v[194:197], v[20:23], v[162:165]
	v_mfma_f32_16x16x32_bf16 v[162:165], v[198:201], v[24:27], v[162:165]
	v_mfma_f32_16x16x32_bf16 v[162:165], v[202:205], v[28:31], v[162:165]
	s_waitcnt vmcnt(28)
	v_lshlrev_b32_e32 v170, 16, v52
	v_and_b32_e32 v171, 0xffff0000, v52
	v_mul_f32_e32 v166, 0xbfb8aa3b, v170
	v_exp_f32_e32 v166, v166
	s_nop 0
	v_add_f32_e32 v166, 1.0, v166
	v_rcp_f32_e32 v172, v166
	v_mul_f32_e32 v166, 0xbfb8aa3b, v171
	v_exp_f32_e32 v166, v166
	s_nop 0
	v_add_f32_e32 v166, 1.0, v166
	v_rcp_f32_e32 v173, v166
	s_waitcnt vmcnt(4)
	v_pk_mul_f32 v[122:123], v[122:123], v[162:163]
	v_pk_mul_f32 v[124:125], v[124:125], v[164:165]
	v_pk_mul_f32 v[172:173], v[172:173], v[170:171]
	s_nop 0
	v_pk_mul_f32 v[122:123], v[172:173], v[122:123]
	s_nop 0
	v_cvt_pk_bf16_f32 v166, v122, v123
	v_lshlrev_b32_e32 v170, 16, v53
	v_and_b32_e32 v171, 0xffff0000, v53
	v_mul_f32_e32 v167, 0xbfb8aa3b, v170
	v_exp_f32_e32 v167, v167
	s_nop 0
	v_add_f32_e32 v167, 1.0, v167
	v_rcp_f32_e32 v172, v167
	v_mul_f32_e32 v167, 0xbfb8aa3b, v171
	v_exp_f32_e32 v167, v167
	s_nop 0
	v_add_f32_e32 v167, 1.0, v167
	v_rcp_f32_e32 v173, v167
	s_nop 1
	v_pk_mul_f32 v[172:173], v[172:173], v[170:171]
	s_nop 0
	v_pk_mul_f32 v[124:125], v[172:173], v[124:125]
	s_nop 0
	v_cvt_pk_bf16_f32 v167, v124, v125
	s_nop 0
	global_store_dwordx2 v[132:133], v[166:167], off offset:2368
	global_load_dwordx4 v[122:125], v[130:131], off offset:832
	s_waitcnt lgkmcnt(0)
	ds_read_b128 v[174:177], v103 offset:33792
	ds_read_b128 v[178:181], v103 offset:33856
	ds_read_b128 v[182:185], v103 offset:33920
	ds_read_b128 v[186:189], v103 offset:33984
	ds_read_b128 v[190:193], v103 offset:34048
	ds_read_b128 v[194:197], v103 offset:34112
	ds_read_b128 v[198:201], v103 offset:34176
	ds_read_b128 v[202:205], v103 offset:34240
	v_mfma_f32_16x16x32_bf16 v[162:165], v[206:209], v[0:3], 0
	v_mfma_f32_16x16x32_bf16 v[162:165], v[210:213], v[4:7], v[162:165]
	v_mfma_f32_16x16x32_bf16 v[162:165], v[214:217], v[8:11], v[162:165]
	v_mfma_f32_16x16x32_bf16 v[162:165], v[218:221], v[12:15], v[162:165]
	v_mfma_f32_16x16x32_bf16 v[162:165], v[222:225], v[16:19], v[162:165]
	v_mfma_f32_16x16x32_bf16 v[162:165], v[226:229], v[20:23], v[162:165]
	v_mfma_f32_16x16x32_bf16 v[162:165], v[230:233], v[24:27], v[162:165]
	v_mfma_f32_16x16x32_bf16 v[162:165], v[234:237], v[28:31], v[162:165]
	s_waitcnt vmcnt(29)
	v_lshlrev_b32_e32 v170, 16, v54
	v_and_b32_e32 v171, 0xffff0000, v54
	v_mul_f32_e32 v166, 0xbfb8aa3b, v170
	v_exp_f32_e32 v166, v166
	s_nop 0
	v_add_f32_e32 v166, 1.0, v166
	v_rcp_f32_e32 v172, v166
	v_mul_f32_e32 v166, 0xbfb8aa3b, v171
	v_exp_f32_e32 v166, v166
	s_nop 0
	v_add_f32_e32 v166, 1.0, v166
	v_rcp_f32_e32 v173, v166
	s_waitcnt vmcnt(4)
	v_pk_mul_f32 v[126:127], v[126:127], v[162:163]
	v_pk_mul_f32 v[128:129], v[128:129], v[164:165]
	v_pk_mul_f32 v[172:173], v[172:173], v[170:171]
	s_nop 0
	v_pk_mul_f32 v[126:127], v[172:173], v[126:127]
	s_nop 0
	v_cvt_pk_bf16_f32 v166, v126, v127
	v_lshlrev_b32_e32 v170, 16, v55
	v_and_b32_e32 v171, 0xffff0000, v55
	v_mul_f32_e32 v167, 0xbfb8aa3b, v170
	v_exp_f32_e32 v167, v167
	s_nop 0
	v_add_f32_e32 v167, 1.0, v167
	v_rcp_f32_e32 v172, v167
	v_mul_f32_e32 v167, 0xbfb8aa3b, v171
	v_exp_f32_e32 v167, v167
	s_nop 0
	v_add_f32_e32 v167, 1.0, v167
	v_rcp_f32_e32 v173, v167
	s_nop 1
	v_pk_mul_f32 v[172:173], v[172:173], v[170:171]
	s_nop 0
	v_pk_mul_f32 v[128:129], v[172:173], v[128:129]
	s_nop 0
	v_cvt_pk_bf16_f32 v167, v128, v129
	s_nop 0
	global_store_dwordx2 v[132:133], v[166:167], off offset:2400
	global_load_dwordx4 v[126:129], v[130:131], off offset:896
	s_waitcnt lgkmcnt(0)
	ds_read_b128 v[206:209], v103 offset:42240
	ds_read_b128 v[210:213], v103 offset:42304
	ds_read_b128 v[214:217], v103 offset:42368
	ds_read_b128 v[218:221], v103 offset:42432
	ds_read_b128 v[222:225], v103 offset:42496
	ds_read_b128 v[226:229], v103 offset:42560
	ds_read_b128 v[230:233], v103 offset:42624
	ds_read_b128 v[234:237], v103 offset:42688
	v_mfma_f32_16x16x32_bf16 v[162:165], v[174:177], v[0:3], 0
	v_mfma_f32_16x16x32_bf16 v[162:165], v[178:181], v[4:7], v[162:165]
	v_mfma_f32_16x16x32_bf16 v[162:165], v[182:185], v[8:11], v[162:165]
	v_mfma_f32_16x16x32_bf16 v[162:165], v[186:189], v[12:15], v[162:165]
	v_mfma_f32_16x16x32_bf16 v[162:165], v[190:193], v[16:19], v[162:165]
	v_mfma_f32_16x16x32_bf16 v[162:165], v[194:197], v[20:23], v[162:165]
	v_mfma_f32_16x16x32_bf16 v[162:165], v[198:201], v[24:27], v[162:165]
	v_mfma_f32_16x16x32_bf16 v[162:165], v[202:205], v[28:31], v[162:165]
	s_waitcnt vmcnt(30)
	v_lshlrev_b32_e32 v170, 16, v56
	v_and_b32_e32 v171, 0xffff0000, v56
	v_mul_f32_e32 v166, 0xbfb8aa3b, v170
	v_exp_f32_e32 v166, v166
	s_nop 0
	v_add_f32_e32 v166, 1.0, v166
	v_rcp_f32_e32 v172, v166
	v_mul_f32_e32 v166, 0xbfb8aa3b, v171
	v_exp_f32_e32 v166, v166
	s_nop 0
	v_add_f32_e32 v166, 1.0, v166
	v_rcp_f32_e32 v173, v166
	s_waitcnt vmcnt(4)
	v_pk_mul_f32 v[118:119], v[118:119], v[162:163]
	v_pk_mul_f32 v[120:121], v[120:121], v[164:165]
	v_pk_mul_f32 v[172:173], v[172:173], v[170:171]
	s_nop 0
	v_pk_mul_f32 v[118:119], v[172:173], v[118:119]
	s_nop 0
	v_cvt_pk_bf16_f32 v166, v118, v119
	v_lshlrev_b32_e32 v170, 16, v57
	v_and_b32_e32 v171, 0xffff0000, v57
	v_mul_f32_e32 v167, 0xbfb8aa3b, v170
	v_exp_f32_e32 v167, v167
	s_nop 0
	v_add_f32_e32 v167, 1.0, v167
	v_rcp_f32_e32 v172, v167
	v_mul_f32_e32 v167, 0xbfb8aa3b, v171
	v_exp_f32_e32 v167, v167
	s_nop 0
	v_add_f32_e32 v167, 1.0, v167
	v_rcp_f32_e32 v173, v167
	s_nop 1
	v_pk_mul_f32 v[172:173], v[172:173], v[170:171]
	s_nop 0
	v_pk_mul_f32 v[120:121], v[172:173], v[120:121]
	s_nop 0
	v_cvt_pk_bf16_f32 v167, v120, v121
	s_nop 0
	global_store_dwordx2 v[132:133], v[166:167], off offset:2432
	global_load_dwordx4 v[118:121], v[130:131], off offset:960
	s_waitcnt lgkmcnt(0)
	ds_read_b128 v[174:177], v103 offset:50688
	ds_read_b128 v[178:181], v103 offset:50752
	ds_read_b128 v[182:185], v103 offset:50816
	ds_read_b128 v[186:189], v103 offset:50880
	ds_read_b128 v[190:193], v103 offset:50944
	ds_read_b128 v[194:197], v103 offset:51008
	ds_read_b128 v[198:201], v103 offset:51072
	ds_read_b128 v[202:205], v103 offset:51136
	v_mfma_f32_16x16x32_bf16 v[162:165], v[206:209], v[0:3], 0
	v_mfma_f32_16x16x32_bf16 v[162:165], v[210:213], v[4:7], v[162:165]
	v_mfma_f32_16x16x32_bf16 v[162:165], v[214:217], v[8:11], v[162:165]
	v_mfma_f32_16x16x32_bf16 v[162:165], v[218:221], v[12:15], v[162:165]
	v_mfma_f32_16x16x32_bf16 v[162:165], v[222:225], v[16:19], v[162:165]
	v_mfma_f32_16x16x32_bf16 v[162:165], v[226:229], v[20:23], v[162:165]
	v_mfma_f32_16x16x32_bf16 v[162:165], v[230:233], v[24:27], v[162:165]
	v_mfma_f32_16x16x32_bf16 v[162:165], v[234:237], v[28:31], v[162:165]
	s_waitcnt vmcnt(31)
	v_lshlrev_b32_e32 v170, 16, v58
	v_and_b32_e32 v171, 0xffff0000, v58
	v_mul_f32_e32 v166, 0xbfb8aa3b, v170
	v_exp_f32_e32 v166, v166
	s_nop 0
	v_add_f32_e32 v166, 1.0, v166
	v_rcp_f32_e32 v172, v166
	v_mul_f32_e32 v166, 0xbfb8aa3b, v171
	v_exp_f32_e32 v166, v166
	s_nop 0
	v_add_f32_e32 v166, 1.0, v166
	v_rcp_f32_e32 v173, v166
	s_waitcnt vmcnt(4)
	v_pk_mul_f32 v[122:123], v[122:123], v[162:163]
	v_pk_mul_f32 v[124:125], v[124:125], v[164:165]
	v_pk_mul_f32 v[172:173], v[172:173], v[170:171]
	s_nop 0
	v_pk_mul_f32 v[122:123], v[172:173], v[122:123]
	s_nop 0
	v_cvt_pk_bf16_f32 v166, v122, v123
	v_lshlrev_b32_e32 v170, 16, v59
	v_and_b32_e32 v171, 0xffff0000, v59
	v_mul_f32_e32 v167, 0xbfb8aa3b, v170
	v_exp_f32_e32 v167, v167
	s_nop 0
	v_add_f32_e32 v167, 1.0, v167
	v_rcp_f32_e32 v172, v167
	v_mul_f32_e32 v167, 0xbfb8aa3b, v171
	v_exp_f32_e32 v167, v167
	s_nop 0
	v_add_f32_e32 v167, 1.0, v167
	v_rcp_f32_e32 v173, v167
	s_nop 1
	v_pk_mul_f32 v[172:173], v[172:173], v[170:171]
	s_nop 0
	v_pk_mul_f32 v[124:125], v[172:173], v[124:125]
	s_nop 0
	v_cvt_pk_bf16_f32 v167, v124, v125
	s_nop 0
	global_store_dwordx2 v[132:133], v[166:167], off offset:2464
	s_waitcnt lgkmcnt(0)
	ds_read_b128 v[206:209], v103 offset:59136
	ds_read_b128 v[210:213], v103 offset:59200
	ds_read_b128 v[214:217], v103 offset:59264
	ds_read_b128 v[218:221], v103 offset:59328
	ds_read_b128 v[222:225], v103 offset:59392
	ds_read_b128 v[226:229], v103 offset:59456
	ds_read_b128 v[230:233], v103 offset:59520
	ds_read_b128 v[234:237], v103 offset:59584
	v_mfma_f32_16x16x32_bf16 v[162:165], v[174:177], v[0:3], 0
	v_mfma_f32_16x16x32_bf16 v[162:165], v[178:181], v[4:7], v[162:165]
	v_mfma_f32_16x16x32_bf16 v[162:165], v[182:185], v[8:11], v[162:165]
	v_mfma_f32_16x16x32_bf16 v[162:165], v[186:189], v[12:15], v[162:165]
	v_mfma_f32_16x16x32_bf16 v[162:165], v[190:193], v[16:19], v[162:165]
	v_mfma_f32_16x16x32_bf16 v[162:165], v[194:197], v[20:23], v[162:165]
	v_mfma_f32_16x16x32_bf16 v[162:165], v[198:201], v[24:27], v[162:165]
	v_mfma_f32_16x16x32_bf16 v[162:165], v[202:205], v[28:31], v[162:165]
	s_waitcnt vmcnt(31)
	v_lshlrev_b32_e32 v170, 16, v60
	v_and_b32_e32 v171, 0xffff0000, v60
	v_mul_f32_e32 v166, 0xbfb8aa3b, v170
	v_exp_f32_e32 v166, v166
	s_nop 0
	v_add_f32_e32 v166, 1.0, v166
	v_rcp_f32_e32 v172, v166
	v_mul_f32_e32 v166, 0xbfb8aa3b, v171
	v_exp_f32_e32 v166, v166
	s_nop 0
	v_add_f32_e32 v166, 1.0, v166
	v_rcp_f32_e32 v173, v166
	s_waitcnt vmcnt(3)
	v_pk_mul_f32 v[126:127], v[126:127], v[162:163]
	v_pk_mul_f32 v[128:129], v[128:129], v[164:165]
	v_pk_mul_f32 v[172:173], v[172:173], v[170:171]
	s_nop 0
	v_pk_mul_f32 v[126:127], v[172:173], v[126:127]
	s_nop 0
	v_cvt_pk_bf16_f32 v166, v126, v127
	v_lshlrev_b32_e32 v170, 16, v61
	v_and_b32_e32 v171, 0xffff0000, v61
	v_mul_f32_e32 v167, 0xbfb8aa3b, v170
	v_exp_f32_e32 v167, v167
	s_nop 0
	v_add_f32_e32 v167, 1.0, v167
	v_rcp_f32_e32 v172, v167
	v_mul_f32_e32 v167, 0xbfb8aa3b, v171
	v_exp_f32_e32 v167, v167
	s_nop 0
	v_add_f32_e32 v167, 1.0, v167
	v_rcp_f32_e32 v173, v167
	s_nop 1
	v_pk_mul_f32 v[172:173], v[172:173], v[170:171]
	s_nop 0
	v_pk_mul_f32 v[128:129], v[172:173], v[128:129]
	s_nop 0
	v_cvt_pk_bf16_f32 v167, v128, v129
	s_nop 0
	global_store_dwordx2 v[132:133], v[166:167], off offset:2496
	s_waitcnt lgkmcnt(0)
	v_mfma_f32_16x16x32_bf16 v[162:165], v[206:209], v[0:3], 0
	v_mfma_f32_16x16x32_bf16 v[162:165], v[210:213], v[4:7], v[162:165]
	v_mfma_f32_16x16x32_bf16 v[162:165], v[214:217], v[8:11], v[162:165]
	v_mfma_f32_16x16x32_bf16 v[162:165], v[218:221], v[12:15], v[162:165]
	v_mfma_f32_16x16x32_bf16 v[162:165], v[222:225], v[16:19], v[162:165]
	v_mfma_f32_16x16x32_bf16 v[162:165], v[226:229], v[20:23], v[162:165]
	v_mfma_f32_16x16x32_bf16 v[162:165], v[230:233], v[24:27], v[162:165]
	v_mfma_f32_16x16x32_bf16 v[162:165], v[234:237], v[28:31], v[162:165]
	s_waitcnt vmcnt(31)
	v_lshlrev_b32_e32 v170, 16, v62
	v_and_b32_e32 v171, 0xffff0000, v62
	v_mul_f32_e32 v166, 0xbfb8aa3b, v170
	v_exp_f32_e32 v166, v166
	s_nop 0
	v_add_f32_e32 v166, 1.0, v166
	v_rcp_f32_e32 v172, v166
	v_mul_f32_e32 v166, 0xbfb8aa3b, v171
	v_exp_f32_e32 v166, v166
	s_nop 0
	v_add_f32_e32 v166, 1.0, v166
	v_rcp_f32_e32 v173, v166
	s_waitcnt vmcnt(2)
	v_pk_mul_f32 v[118:119], v[118:119], v[162:163]
	v_pk_mul_f32 v[120:121], v[120:121], v[164:165]
	v_pk_mul_f32 v[172:173], v[172:173], v[170:171]
	s_nop 0
	v_pk_mul_f32 v[118:119], v[172:173], v[118:119]
	s_nop 0
	v_cvt_pk_bf16_f32 v166, v118, v119
	v_lshlrev_b32_e32 v170, 16, v63
	v_and_b32_e32 v171, 0xffff0000, v63
	v_mul_f32_e32 v167, 0xbfb8aa3b, v170
	v_exp_f32_e32 v167, v167
	s_nop 0
	v_add_f32_e32 v167, 1.0, v167
	v_rcp_f32_e32 v172, v167
	v_mul_f32_e32 v167, 0xbfb8aa3b, v171
	v_exp_f32_e32 v167, v167
	s_nop 0
	v_add_f32_e32 v167, 1.0, v167
	v_rcp_f32_e32 v173, v167
	s_nop 1
	v_pk_mul_f32 v[172:173], v[172:173], v[170:171]
	s_nop 0
	v_pk_mul_f32 v[120:121], v[172:173], v[120:121]
	s_nop 0
	v_cvt_pk_bf16_f32 v167, v120, v121
	s_nop 0
	global_store_dwordx2 v[132:133], v[166:167], off offset:2528
	s_cmp_lg_u32 s0, 0
	s_cbranch_scc1 .LBB0_554
	v_mov_b32_e32 v252, 0x3000
	s_mov_b32 s13, 0
